# idle waves prefetch the first two K-tiles of the next GEMM phase's first weight tile into L2 during the grid barrier (6 seams)
# baseline (speedup 1.0000x reference)
.LBB0_319:
	s_or_b64 exec, exec, s[6:7]
	s_waitcnt vmcnt(0)
	s_branch .LBB0_320
.Lpf_w0:
	s_or_b64 exec, exec, s[4:5]
	s_bfe_u32 s98, s81, 0x20006
	s_mul_i32 s98, s98, 0x80000
	s_add_u32 s98, s98, 0x100000
	s_add_u32 s98, s6, s98
	s_addc_u32 s99, s7, 0
	s_add_u32 s100, s98, 0x400000
	s_addc_u32 s101, s99, 0
	v_subrev_u32_e32 v46, 64, v0
	v_add_u32_e32 v47, 0x1c0, v46
	v_min_u32_e32 v47, 0x1ff, v47
	v_lshrrev_b32_e32 v48, 1, v46
	v_and_b32_e32 v46, 1, v46
	v_lshlrev_b32_e32 v48, 11, v48
	v_lshl_or_b32 v46, v46, 7, v48
	v_lshrrev_b32_e32 v48, 1, v47
	v_and_b32_e32 v47, 1, v47
	v_lshlrev_b32_e32 v48, 11, v48
	v_lshl_or_b32 v47, v47, 7, v48
	global_load_dword v49, v46, s[98:99]
	global_load_dword v50, v47, s[98:99]
	global_load_dword v51, v46, s[100:101]
	global_load_dword v52, v47, s[100:101]
	s_waitcnt vmcnt(0)

.Lpf_w1:
	s_or_b64 exec, exec, s[2:3]
	s_bfe_u32 s98, s81, 0x20006
	s_mul_i32 s98, s98, 0x80000
	s_add_u32 s98, s98, 0x1200000
	s_add_u32 s98, s6, s98
	s_addc_u32 s99, s7, 0
	s_add_u32 s100, s98, 0x800000
	s_addc_u32 s101, s99, 0
	v_subrev_u32_e32 v46, 64, v0
	v_add_u32_e32 v47, 0x1c0, v46
	v_min_u32_e32 v47, 0x1ff, v47
	v_lshrrev_b32_e32 v48, 1, v46
	v_and_b32_e32 v46, 1, v46
	v_lshlrev_b32_e32 v48, 11, v48
	v_lshl_or_b32 v46, v46, 7, v48
	v_lshrrev_b32_e32 v48, 1, v47
	v_and_b32_e32 v47, 1, v47
	v_lshlrev_b32_e32 v48, 11, v48
	v_lshl_or_b32 v47, v47, 7, v48
	global_load_dword v49, v46, s[98:99]
	global_load_dword v50, v47, s[98:99]
	global_load_dword v51, v46, s[100:101]
	global_load_dword v52, v47, s[100:101]
	s_waitcnt vmcnt(0)

.Lpf_w2:
	s_or_b64 exec, exec, s[2:3]
	s_bfe_u32 s98, s81, 0x20006
	s_mul_i32 s98, s98, 0x200000
	s_add_u32 s98, s98, 0x3200000
	s_add_u32 s98, s6, s98
	s_addc_u32 s99, s7, 0
	s_add_u32 s100, s98, 0x800000
	s_addc_u32 s101, s99, 0
	v_subrev_u32_e32 v46, 64, v0
	v_add_u32_e32 v47, 0x1c0, v46
	v_min_u32_e32 v47, 0x1ff, v47
	v_lshrrev_b32_e32 v48, 1, v46
	v_and_b32_e32 v46, 1, v46
	v_lshlrev_b32_e32 v48, 13, v48
	v_lshl_or_b32 v46, v46, 7, v48
	v_lshrrev_b32_e32 v48, 1, v47
	v_and_b32_e32 v47, 1, v47
	v_lshlrev_b32_e32 v48, 13, v48
	v_lshl_or_b32 v47, v47, 7, v48
	global_load_dword v49, v46, s[98:99]
	global_load_dword v50, v47, s[98:99]
	global_load_dword v51, v46, s[100:101]
	global_load_dword v52, v47, s[100:101]
	s_waitcnt vmcnt(0)

.Lpf_w3:
	s_or_b64 exec, exec, s[2:3]
	s_bfe_u32 s98, s81, 0x20006
	s_mul_i32 s98, s98, 0x80000
	s_add_u32 s98, s98, 0xe00000
	s_add_u32 s98, s6, s98
	s_addc_u32 s99, s7, 0
	s_add_u32 s100, s98, 0x200000
	s_addc_u32 s101, s99, 0
	v_subrev_u32_e32 v46, 64, v0
	v_add_u32_e32 v47, 0x1c0, v46
	v_min_u32_e32 v47, 0x1ff, v47
	v_lshrrev_b32_e32 v48, 1, v46
	v_and_b32_e32 v46, 1, v46
	v_lshlrev_b32_e32 v48, 11, v48
	v_lshl_or_b32 v46, v46, 7, v48
	v_lshrrev_b32_e32 v48, 1, v47
	v_and_b32_e32 v47, 1, v47
	v_lshlrev_b32_e32 v48, 11, v48
	v_lshl_or_b32 v47, v47, 7, v48
	global_load_dword v49, v46, s[98:99]
	global_load_dword v50, v47, s[98:99]
	global_load_dword v51, v46, s[100:101]
	global_load_dword v52, v47, s[100:101]
	s_waitcnt vmcnt(0)

.Lpf_w4:
	s_or_b64 exec, exec, s[2:3]
	s_bfe_u32 s98, s81, 0x20006
	s_mul_i32 s98, s98, 0x80000
	s_add_u32 s98, s98, 0x2200000
	s_add_u32 s98, s6, s98
	s_addc_u32 s99, s7, 0
	s_add_u32 s100, s98, 0x800000
	s_addc_u32 s101, s99, 0
	v_subrev_u32_e32 v46, 64, v0
	v_add_u32_e32 v47, 0x1c0, v46
	v_min_u32_e32 v47, 0x1ff, v47
	v_lshrrev_b32_e32 v48, 1, v46
	v_and_b32_e32 v46, 1, v46
	v_lshlrev_b32_e32 v48, 11, v48
	v_lshl_or_b32 v46, v46, 7, v48
	v_lshrrev_b32_e32 v48, 1, v47
	v_and_b32_e32 v47, 1, v47
	v_lshlrev_b32_e32 v48, 11, v48
	v_lshl_or_b32 v47, v47, 7, v48
	global_load_dword v49, v46, s[98:99]
	global_load_dword v50, v47, s[98:99]
	global_load_dword v51, v46, s[100:101]
	global_load_dword v52, v47, s[100:101]
	s_waitcnt vmcnt(0)

.Lpf_w5:
	s_or_b64 exec, exec, s[2:3]
	s_bfe_u32 s98, s81, 0x20006
	s_mul_i32 s98, s98, 0x200000
	s_add_u32 s98, s98, 0x4200000
	s_add_u32 s98, s6, s98
	s_addc_u32 s99, s7, 0
	s_add_u32 s100, s98, 0x800000
	s_addc_u32 s101, s99, 0
	v_subrev_u32_e32 v46, 64, v0
	v_add_u32_e32 v47, 0x1c0, v46
	v_min_u32_e32 v47, 0x1ff, v47
	v_lshrrev_b32_e32 v48, 1, v46
	v_and_b32_e32 v46, 1, v46
	v_lshlrev_b32_e32 v48, 13, v48
	v_lshl_or_b32 v46, v46, 7, v48
	v_lshrrev_b32_e32 v48, 1, v47
	v_and_b32_e32 v47, 1, v47
	v_lshlrev_b32_e32 v48, 13, v48
	v_lshl_or_b32 v47, v47, 7, v48
	global_load_dword v49, v46, s[98:99]
	global_load_dword v50, v47, s[98:99]
	global_load_dword v51, v46, s[100:101]
	global_load_dword v52, v47, s[100:101]
	s_waitcnt vmcnt(0)
